# GEMM unit scheduler: generic signed division by the row-group size (always 8 or 2) replaced by a shift
# baseline (speedup 1.0000x reference)
.LBB0_167:
	s_add_i32 s59, s59, 1
	s_mul_i32 s4, s59, s21
	s_mul_hi_u32 s5, s59, s23
	s_add_i32 s5, s5, s4
	s_mul_i32 s4, s59, s23
	s_add_u32 s46, s4, s76
	s_addc_u32 s47, s5, s60
	v_cmp_gt_i64_e32 vcc, s[46:47], v[146:147]
	v_cmp_lt_i64_e64 s[4:5], s[46:47], v[144:145]
	s_cbranch_vccnz .LBB0_169
	s_ashr_i32 s7, s46, 31
	s_lshr_b32 s7, s7, 29
	s_add_i32 s7, s46, s7
	s_ashr_i32 s29, s7, 3
	s_and_b32 s7, s7, -8
	s_sub_i32 s7, s46, s7
	s_cmp_lt_i32 s7, 0
	s_cselect_b32 s33, s64, 0x186
	s_mul_i32 s7, s7, s33
	s_add_i32 s7, s7, s29
	s_mul_hi_i32 s29, s7, 0x2aaaaaab
	s_lshr_b32 s33, s29, 31
	s_ashr_i32 s29, s29, 5
	s_add_i32 s29, s29, s33
	s_lshl_b32 s33, s29, 3
	s_sub_i32 s34, 0x82, s33
	s_min_i32 s34, s34, 8
	s_mulk_i32 s29, 0xc0
	s_sub_i32 s7, s7, s29
	s_ff1_i32_b32 s35, s34
	s_lshr_b32 s42, s7, s35
	s_mul_i32 s29, s42, s34
	s_sub_i32 s7, s7, s29
	s_add_i32 s44, s33, s7

.LBB0_385:
	s_ashr_i32 s2, s29, 3
	s_add_i32 s2, s35, s2
	s_ashr_i32 s3, s2, 31
	s_lshr_b32 s3, s3, 27
	s_add_i32 s3, s2, s3
	s_ashr_i32 s29, s3, 5
	s_lshl_b32 s29, s29, 3
	s_sub_i32 s34, 0x80, s29
	s_min_i32 s34, s34, 8
	s_andn2_b32 s3, s3, 31
	s_sub_i32 s2, s2, s3
	s_mov_b32 s87, 0
	s_mov_b32 s90, 0
	s_ff1_i32_b32 s35, s34
	s_lshr_b32 s88, s2, s35
	s_mul_i32 s3, s88, s34
	s_sub_i32 s2, s2, s3
	s_add_i32 s89, s29, s2
	s_mov_b64 s[42:43], -1

.LBB0_529:
	s_ashr_i32 s14, s16, 3
	s_add_i32 s14, s18, s14
	s_mul_hi_i32 s15, s14, 0x2e8ba2e9
	s_lshr_b32 s16, s15, 31
	s_ashr_i32 s15, s15, 5
	s_add_i32 s15, s15, s16
	s_lshl_b32 s16, s15, 3
	s_sub_i32 s17, 0x82, s16
	s_min_i32 s17, s17, 8
	s_mulk_i32 s15, 0xb0
	s_sub_i32 s15, s14, s15
	s_ff1_i32_b32 s18, s17
	s_lshr_b32 s14, s15, s18
	s_mul_i32 s17, s14, s17
	s_sub_i32 s15, s15, s17
	s_add_i32 s16, s16, s15

.LBB0_745:
	s_add_i32 s74, s74, 1
	s_mul_i32 s2, s74, s65
	s_mul_hi_u32 s3, s74, s50
	s_add_i32 s3, s3, s2
	s_mul_i32 s2, s74, s50
	s_add_u32 s40, s2, s76
	s_addc_u32 s41, s3, s60
	v_cmp_gt_i64_e32 vcc, s[40:41], v[144:145]
	v_cmp_lt_i64_e64 s[2:3], s[40:41], v[142:143]
	s_cbranch_vccnz .LBB0_747
	s_ashr_i32 s5, s40, 31
	s_lshr_b32 s5, s5, 29
	s_add_i32 s5, s40, s5
	s_ashr_i32 s29, s5, 3
	s_and_b32 s5, s5, -8
	s_sub_i32 s5, s40, s5
	s_cmp_lt_i32 s5, 0
	s_cselect_b32 s33, s66, 0xc3
	s_mul_i32 s5, s5, s33
	s_add_i32 s5, s5, s29
	s_mul_hi_i32 s29, s5, 0x2aaaaaab
	s_lshr_b32 s33, s29, 31
	s_ashr_i32 s29, s29, 4
	s_add_i32 s29, s29, s33
	s_lshl_b32 s33, s29, 3
	s_sub_i32 s34, 0x82, s33
	s_min_i32 s34, s34, 8
	s_mulk_i32 s29, 0x60
	s_sub_i32 s5, s5, s29
	s_ff1_i32_b32 s35, s34
	s_lshr_b32 s36, s5, s35
	s_mul_i32 s29, s36, s34
	s_sub_i32 s5, s5, s29
	s_add_i32 s38, s33, s5

.LBB0_1109:
	s_ashr_i32 s2, s19, 3
	s_add_i32 s2, s34, s2
	s_ashr_i32 s3, s2, 31
	s_lshr_b32 s3, s3, 27
	s_add_i32 s3, s2, s3
	s_ashr_i32 s19, s3, 5
	s_lshl_b32 s19, s19, 3
	s_sub_i32 s29, 0x80, s19
	s_min_i32 s29, s29, 8
	s_andn2_b32 s3, s3, 31
	s_sub_i32 s2, s2, s3
	s_mov_b32 s90, 0
	s_mov_b64 s[50:51], -1
	s_mov_b32 s91, 0
	s_ff1_i32_b32 s34, s29
	s_lshr_b32 s46, s2, s34
	s_mul_i32 s3, s46, s29
	s_sub_i32 s2, s2, s3
	s_add_i32 s48, s19, s2

.LBB0_1469:
	s_add_i32 s84, s84, 1
	s_mul_i32 s2, s84, s66
	s_mul_hi_u32 s3, s84, s50
	s_add_i32 s3, s3, s2
	s_mul_i32 s2, s84, s50
	s_add_u32 s10, s2, s76
	s_addc_u32 s11, s3, s60
	v_cmp_gt_i64_e32 vcc, s[10:11], v[156:157]
	v_cmp_lt_i64_e64 s[2:3], s[10:11], v[154:155]
	s_cbranch_vccnz .LBB0_1471
	s_ashr_i32 s5, s10, 31
	s_lshr_b32 s5, s5, 29
	s_add_i32 s5, s10, s5
	s_ashr_i32 s11, s5, 3
	s_and_b32 s5, s5, -8
	s_sub_i32 s5, s10, s5
	s_cmp_lt_i32 s5, 0
	s_cselect_b32 s10, s67, 0x186
	s_mul_i32 s5, s5, s10
	s_add_i32 s5, s5, s11
	s_mul_hi_i32 s10, s5, 0x2aaaaaab
	s_lshr_b32 s11, s10, 31
	s_ashr_i32 s10, s10, 5
	s_add_i32 s10, s10, s11
	s_lshl_b32 s11, s10, 3
	s_sub_i32 s13, 0x82, s11
	s_min_i32 s13, s13, 8
	s_mulk_i32 s10, 0xc0
	s_sub_i32 s5, s5, s10
	s_ff1_i32_b32 s16, s13
	s_lshr_b32 s38, s5, s16
	s_mul_i32 s10, s38, s13
	s_sub_i32 s5, s5, s10
	s_add_i32 s40, s11, s5

.LBB0_2302:
	s_add_i32 s74, s74, 1
	s_mul_i32 s4, s74, s83
	s_mul_hi_u32 s5, s74, s39
	s_add_i32 s5, s5, s4
	s_mul_i32 s4, s74, s39
	s_add_u32 s60, s4, s76
	s_addc_u32 s61, s5, s75
	v_cmp_gt_i64_e32 vcc, s[60:61], v[148:149]
	v_cmp_lt_i64_e64 s[4:5], s[60:61], v[146:147]
	s_cbranch_vccnz .LBB0_2304
	s_ashr_i32 s9, s60, 31
	s_lshr_b32 s9, s9, 29
	s_add_i32 s9, s60, s9
	s_ashr_i32 s29, s9, 3
	s_and_b32 s9, s9, -8
	s_sub_i32 s9, s60, s9
	s_cmp_lt_i32 s9, 0
	s_cselect_b32 s33, s84, 0x104
	s_mul_i32 s9, s9, s33
	s_add_i32 s9, s9, s29
	s_ashr_i32 s29, s9, 31
	s_lshr_b32 s29, s29, 25
	s_add_i32 s29, s9, s29
	s_ashr_i32 s33, s29, 7
	s_lshl_b32 s33, s33, 3
	s_sub_i32 s34, 0x82, s33
	s_min_i32 s34, s34, 8
	s_and_b32 s29, s29, 0xffffff80
	s_sub_i32 s9, s9, s29
	s_ff1_i32_b32 s35, s34
	s_lshr_b32 s56, s9, s35
	s_mul_i32 s29, s56, s34
	s_sub_i32 s9, s9, s29
	s_add_i32 s58, s33, s9

.LBB0_2591:
	s_ashr_i32 s2, s19, 3
	s_add_i32 s2, s34, s2
	s_ashr_i32 s3, s2, 31
	s_lshr_b32 s3, s3, 27
	s_add_i32 s3, s2, s3
	s_ashr_i32 s19, s3, 5
	s_lshl_b32 s19, s19, 3
	s_sub_i32 s28, 0x80, s19
	s_min_i32 s28, s28, 8
	s_andn2_b32 s3, s3, 31
	s_sub_i32 s2, s2, s3
	s_mov_b32 s90, 0
	s_mov_b64 s[50:51], -1
	s_mov_b32 s91, 0
	s_ff1_i32_b32 s29, s28
	s_lshr_b32 s46, s2, s29
	s_mul_i32 s3, s46, s28
	s_sub_i32 s2, s2, s3
	s_add_i32 s48, s19, s2

.LBB0_2810:
	s_ashr_i32 s2, s29, 3
	s_add_i32 s2, s35, s2
	s_ashr_i32 s3, s2, 31
	s_lshr_b32 s3, s3, 27
	s_add_i32 s3, s2, s3
	s_ashr_i32 s28, s3, 5
	s_lshl_b32 s28, s28, 3
	s_sub_i32 s29, 0x80, s28
	s_min_i32 s29, s29, 8
	s_andn2_b32 s3, s3, 31
	s_sub_i32 s2, s2, s3
	s_mov_b32 s87, 0
	s_mov_b32 s90, 0
	s_ff1_i32_b32 s34, s29
	s_lshr_b32 s88, s2, s34
	s_mul_i32 s3, s88, s29
	s_sub_i32 s2, s2, s3
	s_add_i32 s89, s28, s2
	s_mov_b64 s[42:43], -1
